# deferred weight items in MIX2 now only on the workgroups that have no attention items (scan workgroups left alone)
# speedup vs baseline: 1.0135x; 1.0070x over previous
.Lsc_m2w:
	s_sub_i32 s55, s45, 225
	s_cmp_lt_u32 s45, 225
	s_cbranch_scc1 .Lsc_done
.Lsc_m2w_go:
	s_lshl_b32 s55, s55, 3
	s_add_i32 s55, s55, s46
	s_movk_i32 s30, 248
	s_mul_i32 s67, s47, 0x1200
	s_add_i32 s64, s67, 0x7c0
	s_add_i32 s31, s67, 0xc50
